# P0: transposed bf16 weight stores (full 128-B lines) written through (sc1), shorter L2 write-back at barrier 1
# speedup vs baseline: 1.0054x; 1.0033x over previous
; __device__ __forceinline__ unsigned cvt_pk_bf16(float lo, float hi) { unsigned r; asm("v_cvt_pk_bf16_f32 %0, %1, %2" : "=v"(r) : "v"(lo), "v"(hi)); return r; }
; template <bool PERMW, bool PERM32>
; __device__ __forceinline__ void transpose_cvt(const float* __restrict__ src, bf16_t* __restrict__ dst, int K, int N, float* T, int& tile_ctr, int blk, int nblk) {
;     ...
;     for (int tl = tl0; tl < ntiles; tl += nblk) {
;         const int k0 = (tl % nkt) * 64, n0 = (tl / nkt) * 256;
;         { const int n4 = (tid & 63) * 4, sc = PERMW ? win_src_col(n0 + n4) : n0 + n4; f32x4 v[8];
; #pragma unroll
;           for (int i = 0; i < 8; ++i) { const int k = (tid >> 6) + 8 * i; v[i] = *(const f32x4*)(src + (size_t)(k0 + k) * N + sc); }
; #pragma unroll
;           for (int i = 0; i < 8; ++i) { const int k = (tid >> 6) + 8 * i; *(f32x4*)(T + k * 256 + (n4 ^ (((k >> 3) & 7) << 2))) = v[i]; } }
;         __syncthreads();
; #pragma unroll
;         for (int i = 0; i < 4; ++i) { const int pi = tid + 512 * i, q = pi & 7, nl = pi >> 3, x = PERM32 ? (nl & ~31) + perm32(nl & 31) : nl; const float* tp = T + (8 * q) * 256 + (x ^ (q << 2)); uint4 o;
;             o.x = cvt_pk_bf16(tp[0], tp[256]); o.y = cvt_pk_bf16(tp[512], tp[768]); o.z = cvt_pk_bf16(tp[1024], tp[1280]); o.w = cvt_pk_bf16(tp[1536], tp[1792]);
;             *(uint4*)(dst + (size_t)(n0 + nl) * K + k0 + 8 * q) = o; }
;         __syncthreads();
.LBB0_25:
	s_lshl_b32 s14, s73, 10
	s_sub_i32 s14, s70, s14
	v_add_u32_e32 v52, s14, v10
	v_ashrrev_i32_e32 v7, 31, v6
	v_lshl_add_u64 v[6:7], v[6:7], 2, s[16:17]
	v_add_u32_e32 v28, 8, v52
	v_add_u32_e32 v34, 16, v52
	v_add_u32_e32 v36, 24, v52
	v_add_u32_e32 v42, 32, v52
	v_add_u32_e32 v44, 40, v52
	v_add_u32_e32 v50, 48, v52
	v_mad_i64_i32 v[26:27], s[74:75], v52, s67, v[6:7]
	v_mad_i64_i32 v[30:31], s[74:75], v28, s67, v[6:7]
	v_mad_i64_i32 v[34:35], s[74:75], v34, s67, v[6:7]
	v_mad_i64_i32 v[38:39], s[74:75], v36, s67, v[6:7]
	v_mad_i64_i32 v[42:43], s[74:75], v42, s67, v[6:7]
	v_mad_i64_i32 v[46:47], s[74:75], v44, s67, v[6:7]
	v_mad_i64_i32 v[50:51], s[74:75], v50, s67, v[6:7]
	v_add_u32_e32 v52, 56, v52
	global_load_dwordx4 v[26:29], v[26:27], off nt
	s_nop 0
	global_load_dwordx4 v[30:33], v[30:31], off nt
	s_nop 0
	global_load_dwordx4 v[34:37], v[34:35], off nt
	s_nop 0
	global_load_dwordx4 v[38:41], v[38:39], off nt
	s_nop 0
	global_load_dwordx4 v[42:45], v[42:43], off nt
	s_nop 0
	global_load_dwordx4 v[46:49], v[46:47], off nt
	v_mad_i64_i32 v[6:7], s[74:75], v52, s67, v[6:7]
	global_load_dwordx4 v[50:53], v[50:51], off nt
	s_nop 0
	global_load_dwordx4 v[54:57], v[6:7], off nt
	v_add_u32_e32 v6, s72, v2
	v_add_u32_e32 v58, s72, v20
	v_add_u32_e32 v60, s72, v22
	v_ashrrev_i32_e32 v7, 31, v6
	s_ashr_i32 s15, s14, 31
	v_ashrrev_i32_e32 v59, 31, v58
	v_ashrrev_i32_e32 v61, 31, v60
	v_lshlrev_b64 v[6:7], 11, v[6:7]
	v_lshl_add_u64 v[62:63], s[14:15], 1, v[4:5]
	v_lshlrev_b64 v[58:59], 11, v[58:59]
	v_lshlrev_b64 v[60:61], 11, v[60:61]
	v_lshl_add_u64 v[6:7], v[62:63], 0, v[6:7]
	v_lshl_add_u64 v[58:59], v[62:63], 0, v[58:59]
	v_lshl_add_u64 v[60:61], v[62:63], 0, v[60:61]
	s_add_i32 s69, s69, s33
	s_add_i32 s70, s70, s71
	s_cmpk_lt_i32 s69, 0xa0
	s_waitcnt vmcnt(7)
	ds_write_b128 v12, v[26:29]
	s_waitcnt vmcnt(6)
	ds_write_b128 v13, v[30:33]
	s_waitcnt vmcnt(5)
	ds_write_b128 v14, v[34:37]
	s_waitcnt vmcnt(4)
	ds_write_b128 v15, v[38:41]
	s_waitcnt vmcnt(3)
	ds_write_b128 v16, v[42:45]
	s_waitcnt vmcnt(2)
	ds_write_b128 v17, v[46:49]
	s_waitcnt vmcnt(1)
	ds_write_b128 v18, v[50:53]
	s_waitcnt vmcnt(0)
	ds_write_b128 v19, v[54:57]
	s_waitcnt lgkmcnt(0)
	s_barrier
	ds_read2st64_b32 v[26:27], v11 offset1:4
	ds_read2st64_b32 v[28:29], v11 offset0:8 offset1:12
	ds_read2st64_b32 v[30:31], v11 offset0:16 offset1:20
	ds_read2st64_b32 v[32:33], v11 offset0:24 offset1:28
	ds_read2st64_b32 v[34:35], v21 offset1:4
	ds_read2st64_b32 v[36:37], v21 offset0:8 offset1:12
	ds_read2st64_b32 v[38:39], v21 offset0:16 offset1:20
	ds_read2st64_b32 v[40:41], v21 offset0:24 offset1:28
	ds_read2st64_b32 v[42:43], v23 offset1:4
	ds_read2st64_b32 v[44:45], v23 offset0:8 offset1:12
	ds_read2st64_b32 v[46:47], v23 offset0:16 offset1:20
	ds_read2st64_b32 v[48:49], v23 offset0:24 offset1:28
	ds_read2st64_b32 v[50:51], v25 offset1:4
	ds_read2st64_b32 v[52:53], v25 offset0:8 offset1:12
	ds_read2st64_b32 v[54:55], v25 offset0:16 offset1:20
	ds_read2st64_b32 v[56:57], v25 offset0:24 offset1:28
	s_waitcnt lgkmcnt(14)
	v_cvt_pk_bf16_f32 v26, v26, v27
	v_cvt_pk_bf16_f32 v27, v28, v29
	s_waitcnt lgkmcnt(13)
	v_cvt_pk_bf16_f32 v28, v30, v31
	s_waitcnt lgkmcnt(12)
	v_cvt_pk_bf16_f32 v29, v32, v33
	s_waitcnt lgkmcnt(11)
	v_cvt_pk_bf16_f32 v30, v34, v35
	s_waitcnt lgkmcnt(10)
	v_cvt_pk_bf16_f32 v31, v36, v37
	s_waitcnt lgkmcnt(9)
	v_cvt_pk_bf16_f32 v32, v38, v39
	s_waitcnt lgkmcnt(8)
	v_cvt_pk_bf16_f32 v33, v40, v41
	s_waitcnt lgkmcnt(7)
	v_cvt_pk_bf16_f32 v34, v42, v43
	s_waitcnt lgkmcnt(6)
	v_cvt_pk_bf16_f32 v35, v44, v45
	s_waitcnt lgkmcnt(5)
	v_cvt_pk_bf16_f32 v36, v46, v47
	s_waitcnt lgkmcnt(4)
	v_cvt_pk_bf16_f32 v37, v48, v49
	global_store_dwordx4 v[6:7], v[26:29], off sc1
	global_store_dwordx4 v[58:59], v[30:33], off sc1
	global_store_dwordx4 v[60:61], v[34:37], off sc1
	v_add_u32_e32 v6, s72, v24
	v_ashrrev_i32_e32 v7, 31, v6
	v_lshlrev_b64 v[6:7], 11, v[6:7]
	v_lshl_add_u64 v[6:7], v[62:63], 0, v[6:7]
	s_waitcnt lgkmcnt(3)
	v_cvt_pk_bf16_f32 v26, v50, v51
	s_waitcnt lgkmcnt(2)
	v_cvt_pk_bf16_f32 v27, v52, v53
	s_waitcnt lgkmcnt(1)
	v_cvt_pk_bf16_f32 v28, v54, v55
	s_waitcnt lgkmcnt(0)
	v_cvt_pk_bf16_f32 v29, v56, v57
	global_store_dwordx4 v[6:7], v[26:29], off sc1
	s_barrier
	s_cbranch_scc0 .LBB0_31

; __device__ __forceinline__ unsigned cvt_pk_bf16(float lo, float hi) { unsigned r; asm("v_cvt_pk_bf16_f32 %0, %1, %2" : "=v"(r) : "v"(lo), "v"(hi)); return r; }
; template <bool PERMW, bool PERM32>
; __device__ __forceinline__ void transpose_cvt(const float* __restrict__ src, bf16_t* __restrict__ dst, int K, int N, float* T, int& tile_ctr, int blk, int nblk) {
;     ...
;     for (int tl = tl0; tl < ntiles; tl += nblk) {
;         const int k0 = (tl % nkt) * 64, n0 = (tl / nkt) * 256;
;         { const int n4 = (tid & 63) * 4, sc = PERMW ? win_src_col(n0 + n4) : n0 + n4; f32x4 v[8];
; #pragma unroll
;           for (int i = 0; i < 8; ++i) { const int k = (tid >> 6) + 8 * i; v[i] = *(const f32x4*)(src + (size_t)(k0 + k) * N + sc); }
; #pragma unroll
;           for (int i = 0; i < 8; ++i) { const int k = (tid >> 6) + 8 * i; *(f32x4*)(T + k * 256 + (n4 ^ (((k >> 3) & 7) << 2))) = v[i]; } }
;         __syncthreads();
; #pragma unroll
;         for (int i = 0; i < 4; ++i) { const int pi = tid + 512 * i, q = pi & 7, nl = pi >> 3, x = PERM32 ? (nl & ~31) + perm32(nl & 31) : nl; const float* tp = T + (8 * q) * 256 + (x ^ (q << 2)); uint4 o;
;             o.x = cvt_pk_bf16(tp[0], tp[256]); o.y = cvt_pk_bf16(tp[512], tp[768]); o.z = cvt_pk_bf16(tp[1024], tp[1280]); o.w = cvt_pk_bf16(tp[1536], tp[1792]);
;             *(uint4*)(dst + (size_t)(n0 + nl) * K + k0 + 8 * q) = o; }
;         __syncthreads();
.LBB0_33:
	s_ashr_i32 s14, s69, 31
	s_lshr_b32 s14, s14, 28
	s_add_i32 s14, s69, s14
	s_ashr_i32 s14, s14, 4
	s_lshl_b32 s72, s14, 10
	s_lshl_b32 s15, s14, 8
	s_sub_i32 s14, s70, s72
	v_add_u32_e32 v24, s14, v6
	v_or_b32_e32 v22, s15, v1
	v_add_u32_e32 v26, 8, v24
	v_add_u32_e32 v28, 16, v24
	v_add_u32_e32 v30, 24, v24
	v_add_u32_e32 v32, 32, v24
	v_add_u32_e32 v34, 40, v24
	v_add_u32_e32 v36, 48, v24
	v_add_u32_e32 v38, 56, v24
	v_ashrrev_i32_e32 v23, 31, v22
	v_ashrrev_i32_e32 v25, 31, v24
	v_ashrrev_i32_e32 v27, 31, v26
	v_ashrrev_i32_e32 v29, 31, v28
	v_ashrrev_i32_e32 v31, 31, v30
	v_ashrrev_i32_e32 v33, 31, v32
	v_ashrrev_i32_e32 v35, 31, v34
	v_ashrrev_i32_e32 v37, 31, v36
	v_ashrrev_i32_e32 v39, 31, v38
	v_lshl_add_u64 v[22:23], v[22:23], 2, s[26:27]
	v_lshlrev_b64 v[24:25], 12, v[24:25]
	v_lshlrev_b64 v[26:27], 12, v[26:27]
	v_lshlrev_b64 v[28:29], 12, v[28:29]
	v_lshlrev_b64 v[30:31], 12, v[30:31]
	v_lshlrev_b64 v[32:33], 12, v[32:33]
	v_lshlrev_b64 v[34:35], 12, v[34:35]
	v_lshlrev_b64 v[36:37], 12, v[36:37]
	v_lshlrev_b64 v[38:39], 12, v[38:39]
	v_lshl_add_u64 v[24:25], v[22:23], 0, v[24:25]
	v_lshl_add_u64 v[26:27], v[22:23], 0, v[26:27]
	v_lshl_add_u64 v[40:41], v[22:23], 0, v[28:29]
	v_lshl_add_u64 v[42:43], v[22:23], 0, v[30:31]
	v_lshl_add_u64 v[44:45], v[22:23], 0, v[32:33]
	v_lshl_add_u64 v[46:47], v[22:23], 0, v[34:35]
	v_lshl_add_u64 v[48:49], v[22:23], 0, v[36:37]
	v_lshl_add_u64 v[50:51], v[22:23], 0, v[38:39]
	global_load_dwordx4 v[22:25], v[24:25], off nt
	s_nop 0
	global_load_dwordx4 v[26:29], v[26:27], off nt
	s_nop 0
	global_load_dwordx4 v[30:33], v[40:41], off nt
	global_load_dwordx4 v[34:37], v[42:43], off nt
	s_nop 0
	global_load_dwordx4 v[38:41], v[44:45], off nt
	s_nop 0
	global_load_dwordx4 v[42:45], v[46:47], off nt
	s_nop 0
	global_load_dwordx4 v[46:49], v[48:49], off nt
	s_nop 0
	global_load_dwordx4 v[50:53], v[50:51], off nt
	v_add_u32_e32 v54, s15, v2
	v_add_u32_e32 v56, s15, v16
	v_add_u32_e32 v58, s15, v18
	v_add_u32_e32 v60, s15, v20
	s_ashr_i32 s15, s14, 31
	v_ashrrev_i32_e32 v55, 31, v54
	s_add_i32 s69, s69, s33
	s_add_i32 s70, s70, s71
	v_ashrrev_i32_e32 v57, 31, v56
	v_ashrrev_i32_e32 v59, 31, v58
	v_ashrrev_i32_e32 v61, 31, v60
	v_lshl_add_u64 v[62:63], s[14:15], 1, v[4:5]
	v_lshlrev_b64 v[54:55], 11, v[54:55]
	v_lshlrev_b64 v[56:57], 11, v[56:57]
	v_lshlrev_b64 v[58:59], 11, v[58:59]
	v_lshlrev_b64 v[60:61], 11, v[60:61]
	s_cmp_lt_i32 s69, 64
	v_lshl_add_u64 v[54:55], v[62:63], 0, v[54:55]
	v_lshl_add_u64 v[56:57], v[62:63], 0, v[56:57]
	v_lshl_add_u64 v[58:59], v[62:63], 0, v[58:59]
	v_lshl_add_u64 v[60:61], v[62:63], 0, v[60:61]
	s_waitcnt vmcnt(7)
	ds_write_b128 v8, v[22:25]
	s_waitcnt vmcnt(6)
	ds_write_b128 v9, v[26:29]
	s_waitcnt vmcnt(5)
	ds_write_b128 v10, v[30:33]
	s_waitcnt vmcnt(4)
	ds_write_b128 v11, v[34:37]
	s_waitcnt vmcnt(3)
	ds_write_b128 v12, v[38:41]
	s_waitcnt vmcnt(2)
	ds_write_b128 v13, v[42:45]
	s_waitcnt vmcnt(1)
	ds_write_b128 v14, v[46:49]
	s_waitcnt vmcnt(0)
	ds_write_b128 v15, v[50:53]
	s_waitcnt lgkmcnt(0)
	s_barrier
	ds_read2st64_b32 v[22:23], v7 offset1:4
	ds_read2st64_b32 v[24:25], v7 offset0:8 offset1:12
	ds_read2st64_b32 v[26:27], v7 offset0:16 offset1:20
	ds_read2st64_b32 v[28:29], v7 offset0:24 offset1:28
	ds_read2st64_b32 v[30:31], v17 offset1:4
	ds_read2st64_b32 v[32:33], v17 offset0:8 offset1:12
	ds_read2st64_b32 v[34:35], v17 offset0:16 offset1:20
	ds_read2st64_b32 v[36:37], v17 offset0:24 offset1:28
	ds_read2st64_b32 v[38:39], v19 offset1:4
	ds_read2st64_b32 v[40:41], v19 offset0:8 offset1:12
	ds_read2st64_b32 v[42:43], v19 offset0:16 offset1:20
	ds_read2st64_b32 v[44:45], v19 offset0:24 offset1:28
	ds_read2st64_b32 v[46:47], v21 offset1:4
	ds_read2st64_b32 v[48:49], v21 offset0:8 offset1:12
	ds_read2st64_b32 v[50:51], v21 offset0:16 offset1:20
	ds_read2st64_b32 v[52:53], v21 offset0:24 offset1:28
	s_waitcnt lgkmcnt(14)
	v_cvt_pk_bf16_f32 v22, v22, v23
	v_cvt_pk_bf16_f32 v23, v24, v25
	s_waitcnt lgkmcnt(13)
	v_cvt_pk_bf16_f32 v24, v26, v27
	s_waitcnt lgkmcnt(12)
	v_cvt_pk_bf16_f32 v25, v28, v29
	s_waitcnt lgkmcnt(11)
	v_cvt_pk_bf16_f32 v26, v30, v31
	s_waitcnt lgkmcnt(10)
	v_cvt_pk_bf16_f32 v27, v32, v33
	s_waitcnt lgkmcnt(9)
	v_cvt_pk_bf16_f32 v28, v34, v35
	s_waitcnt lgkmcnt(8)
	v_cvt_pk_bf16_f32 v29, v36, v37
	s_waitcnt lgkmcnt(7)
	v_cvt_pk_bf16_f32 v30, v38, v39
	s_waitcnt lgkmcnt(6)
	v_cvt_pk_bf16_f32 v31, v40, v41
	s_waitcnt lgkmcnt(5)
	v_cvt_pk_bf16_f32 v32, v42, v43
	s_waitcnt lgkmcnt(4)
	v_cvt_pk_bf16_f32 v33, v44, v45
	s_waitcnt lgkmcnt(3)
	v_cvt_pk_bf16_f32 v34, v46, v47
	s_waitcnt lgkmcnt(2)
	v_cvt_pk_bf16_f32 v35, v48, v49
	s_waitcnt lgkmcnt(1)
	v_cvt_pk_bf16_f32 v36, v50, v51
	s_waitcnt lgkmcnt(0)
	v_cvt_pk_bf16_f32 v37, v52, v53
	global_store_dwordx4 v[54:55], v[22:25], off sc1
	global_store_dwordx4 v[56:57], v[26:29], off sc1
	global_store_dwordx4 v[58:59], v[30:33], off sc1
	global_store_dwordx4 v[60:61], v[34:37], off sc1
	s_barrier
	s_cbranch_scc1 .LBB0_33

; __device__ __forceinline__ unsigned cvt_pk_bf16(float lo, float hi) { unsigned r; asm("v_cvt_pk_bf16_f32 %0, %1, %2" : "=v"(r) : "v"(lo), "v"(hi)); return r; }
; template <bool PERMW, bool PERM32>
; __device__ __forceinline__ void transpose_cvt(const float* __restrict__ src, bf16_t* __restrict__ dst, int K, int N, float* T, int& tile_ctr, int blk, int nblk) {
;     ...
;     for (int tl = tl0; tl < ntiles; tl += nblk) {
;         const int k0 = (tl % nkt) * 64, n0 = (tl / nkt) * 256;
;         { const int n4 = (tid & 63) * 4, sc = PERMW ? win_src_col(n0 + n4) : n0 + n4; f32x4 v[8];
; #pragma unroll
;           for (int i = 0; i < 8; ++i) { const int k = (tid >> 6) + 8 * i; v[i] = *(const f32x4*)(src + (size_t)(k0 + k) * N + sc); }
; #pragma unroll
;           for (int i = 0; i < 8; ++i) { const int k = (tid >> 6) + 8 * i; *(f32x4*)(T + k * 256 + (n4 ^ (((k >> 3) & 7) << 2))) = v[i]; } }
;         __syncthreads();
; #pragma unroll
;         for (int i = 0; i < 4; ++i) { const int pi = tid + 512 * i, q = pi & 7, nl = pi >> 3, x = PERM32 ? (nl & ~31) + perm32(nl & 31) : nl; const float* tp = T + (8 * q) * 256 + (x ^ (q << 2)); uint4 o;
;             o.x = cvt_pk_bf16(tp[0], tp[256]); o.y = cvt_pk_bf16(tp[512], tp[768]); o.z = cvt_pk_bf16(tp[1024], tp[1280]); o.w = cvt_pk_bf16(tp[1536], tp[1792]);
;             *(uint4*)(dst + (size_t)(n0 + nl) * K + k0 + 8 * q) = o; }
;         __syncthreads();
.LBB0_36:
	s_ashr_i32 s14, s69, 31
	s_lshr_b32 s14, s14, 26
	s_add_i32 s14, s69, s14
	s_ashr_i32 s14, s14, 6
	s_lshl_b32 s72, s14, 12
	s_lshl_b32 s15, s14, 8
	s_sub_i32 s14, s70, s72
	v_add_u32_e32 v24, s14, v6
	v_or_b32_e32 v22, s15, v1
	v_add_u32_e32 v26, 8, v24
	v_add_u32_e32 v28, 16, v24
	v_add_u32_e32 v30, 24, v24
	v_add_u32_e32 v32, 32, v24
	v_add_u32_e32 v34, 40, v24
	v_add_u32_e32 v36, 48, v24
	v_add_u32_e32 v38, 56, v24
	v_ashrrev_i32_e32 v23, 31, v22
	v_ashrrev_i32_e32 v25, 31, v24
	v_ashrrev_i32_e32 v27, 31, v26
	v_ashrrev_i32_e32 v29, 31, v28
	v_ashrrev_i32_e32 v31, 31, v30
	v_ashrrev_i32_e32 v33, 31, v32
	v_ashrrev_i32_e32 v35, 31, v34
	v_ashrrev_i32_e32 v37, 31, v36
	v_ashrrev_i32_e32 v39, 31, v38
	v_lshl_add_u64 v[22:23], v[22:23], 2, s[52:53]
	v_lshlrev_b64 v[24:25], 12, v[24:25]
	v_lshlrev_b64 v[26:27], 12, v[26:27]
	v_lshlrev_b64 v[28:29], 12, v[28:29]
	v_lshlrev_b64 v[30:31], 12, v[30:31]
	v_lshlrev_b64 v[32:33], 12, v[32:33]
	v_lshlrev_b64 v[34:35], 12, v[34:35]
	v_lshlrev_b64 v[36:37], 12, v[36:37]
	v_lshlrev_b64 v[38:39], 12, v[38:39]
	v_lshl_add_u64 v[24:25], v[22:23], 0, v[24:25]
	v_lshl_add_u64 v[26:27], v[22:23], 0, v[26:27]
	v_lshl_add_u64 v[40:41], v[22:23], 0, v[28:29]
	v_lshl_add_u64 v[42:43], v[22:23], 0, v[30:31]
	v_lshl_add_u64 v[44:45], v[22:23], 0, v[32:33]
	v_lshl_add_u64 v[46:47], v[22:23], 0, v[34:35]
	v_lshl_add_u64 v[48:49], v[22:23], 0, v[36:37]
	v_lshl_add_u64 v[50:51], v[22:23], 0, v[38:39]
	global_load_dwordx4 v[22:25], v[24:25], off nt
	s_nop 0
	global_load_dwordx4 v[26:29], v[26:27], off nt
	s_nop 0
	global_load_dwordx4 v[30:33], v[40:41], off nt
	global_load_dwordx4 v[34:37], v[42:43], off nt
	s_nop 0
	global_load_dwordx4 v[38:41], v[44:45], off nt
	s_nop 0
	global_load_dwordx4 v[42:45], v[46:47], off nt
	s_nop 0
	global_load_dwordx4 v[46:49], v[48:49], off nt
	s_nop 0
	global_load_dwordx4 v[50:53], v[50:51], off nt
	v_add_u32_e32 v54, s15, v2
	v_add_u32_e32 v56, s15, v16
	v_add_u32_e32 v58, s15, v18
	v_add_u32_e32 v60, s15, v20
	s_ashr_i32 s15, s14, 31
	v_ashrrev_i32_e32 v55, 31, v54
	s_add_i32 s69, s69, s33
	s_add_i32 s70, s70, s71
	v_ashrrev_i32_e32 v57, 31, v56
	v_ashrrev_i32_e32 v59, 31, v58
	v_ashrrev_i32_e32 v61, 31, v60
	v_lshl_add_u64 v[62:63], s[14:15], 1, v[4:5]
	v_lshlrev_b64 v[54:55], 13, v[54:55]
	v_lshlrev_b64 v[56:57], 13, v[56:57]
	v_lshlrev_b64 v[58:59], 13, v[58:59]
	v_lshlrev_b64 v[60:61], 13, v[60:61]
	s_cmpk_lt_i32 s69, 0x100
	v_lshl_add_u64 v[54:55], v[62:63], 0, v[54:55]
	v_lshl_add_u64 v[56:57], v[62:63], 0, v[56:57]
	v_lshl_add_u64 v[58:59], v[62:63], 0, v[58:59]
	v_lshl_add_u64 v[60:61], v[62:63], 0, v[60:61]
	s_waitcnt vmcnt(7)
	ds_write_b128 v8, v[22:25]
	s_waitcnt vmcnt(6)
	ds_write_b128 v9, v[26:29]
	s_waitcnt vmcnt(5)
	ds_write_b128 v10, v[30:33]
	s_waitcnt vmcnt(4)
	ds_write_b128 v11, v[34:37]
	s_waitcnt vmcnt(3)
	ds_write_b128 v12, v[38:41]
	s_waitcnt vmcnt(2)
	ds_write_b128 v13, v[42:45]
	s_waitcnt vmcnt(1)
	ds_write_b128 v14, v[46:49]
	s_waitcnt vmcnt(0)
	ds_write_b128 v15, v[50:53]
	s_waitcnt lgkmcnt(0)
	s_barrier
	ds_read2st64_b32 v[22:23], v7 offset1:4
	ds_read2st64_b32 v[24:25], v7 offset0:8 offset1:12
	ds_read2st64_b32 v[26:27], v7 offset0:16 offset1:20
	ds_read2st64_b32 v[28:29], v7 offset0:24 offset1:28
	ds_read2st64_b32 v[30:31], v17 offset1:4
	ds_read2st64_b32 v[32:33], v17 offset0:8 offset1:12
	ds_read2st64_b32 v[34:35], v17 offset0:16 offset1:20
	ds_read2st64_b32 v[36:37], v17 offset0:24 offset1:28
	ds_read2st64_b32 v[38:39], v19 offset1:4
	ds_read2st64_b32 v[40:41], v19 offset0:8 offset1:12
	ds_read2st64_b32 v[42:43], v19 offset0:16 offset1:20
	ds_read2st64_b32 v[44:45], v19 offset0:24 offset1:28
	ds_read2st64_b32 v[46:47], v21 offset1:4
	ds_read2st64_b32 v[48:49], v21 offset0:8 offset1:12
	ds_read2st64_b32 v[50:51], v21 offset0:16 offset1:20
	ds_read2st64_b32 v[52:53], v21 offset0:24 offset1:28
	s_waitcnt lgkmcnt(14)
	v_cvt_pk_bf16_f32 v22, v22, v23
	v_cvt_pk_bf16_f32 v23, v24, v25
	s_waitcnt lgkmcnt(13)
	v_cvt_pk_bf16_f32 v24, v26, v27
	s_waitcnt lgkmcnt(12)
	v_cvt_pk_bf16_f32 v25, v28, v29
	s_waitcnt lgkmcnt(11)
	v_cvt_pk_bf16_f32 v26, v30, v31
	s_waitcnt lgkmcnt(10)
	v_cvt_pk_bf16_f32 v27, v32, v33
	s_waitcnt lgkmcnt(9)
	v_cvt_pk_bf16_f32 v28, v34, v35
	s_waitcnt lgkmcnt(8)
	v_cvt_pk_bf16_f32 v29, v36, v37
	s_waitcnt lgkmcnt(7)
	v_cvt_pk_bf16_f32 v30, v38, v39
	s_waitcnt lgkmcnt(6)
	v_cvt_pk_bf16_f32 v31, v40, v41
	s_waitcnt lgkmcnt(5)
	v_cvt_pk_bf16_f32 v32, v42, v43
	s_waitcnt lgkmcnt(4)
	v_cvt_pk_bf16_f32 v33, v44, v45
	s_waitcnt lgkmcnt(3)
	v_cvt_pk_bf16_f32 v34, v46, v47
	s_waitcnt lgkmcnt(2)
	v_cvt_pk_bf16_f32 v35, v48, v49
	s_waitcnt lgkmcnt(1)
	v_cvt_pk_bf16_f32 v36, v50, v51
	s_waitcnt lgkmcnt(0)
	v_cvt_pk_bf16_f32 v37, v52, v53
	global_store_dwordx4 v[54:55], v[22:25], off sc1
	global_store_dwordx4 v[56:57], v[26:29], off sc1
	global_store_dwordx4 v[58:59], v[30:33], off sc1
	global_store_dwordx4 v[60:61], v[34:37], off sc1
	s_barrier
	s_cbranch_scc1 .LBB0_36

; __device__ __forceinline__ unsigned cvt_pk_bf16(float lo, float hi) { unsigned r; asm("v_cvt_pk_bf16_f32 %0, %1, %2" : "=v"(r) : "v"(lo), "v"(hi)); return r; }
; template <bool PERMW, bool PERM32>
; __device__ __forceinline__ void transpose_cvt(const float* __restrict__ src, bf16_t* __restrict__ dst, int K, int N, float* T, int& tile_ctr, int blk, int nblk) {
;     ...
;     for (int tl = tl0; tl < ntiles; tl += nblk) {
;         const int k0 = (tl % nkt) * 64, n0 = (tl / nkt) * 256;
;         { const int n4 = (tid & 63) * 4, sc = PERMW ? win_src_col(n0 + n4) : n0 + n4; f32x4 v[8];
; #pragma unroll
;           for (int i = 0; i < 8; ++i) { const int k = (tid >> 6) + 8 * i; v[i] = *(const f32x4*)(src + (size_t)(k0 + k) * N + sc); }
; #pragma unroll
;           for (int i = 0; i < 8; ++i) { const int k = (tid >> 6) + 8 * i; *(f32x4*)(T + k * 256 + (n4 ^ (((k >> 3) & 7) << 2))) = v[i]; } }
;         __syncthreads();
; #pragma unroll
;         for (int i = 0; i < 4; ++i) { const int pi = tid + 512 * i, q = pi & 7, nl = pi >> 3, x = PERM32 ? (nl & ~31) + perm32(nl & 31) : nl; const float* tp = T + (8 * q) * 256 + (x ^ (q << 2)); uint4 o;
;             o.x = cvt_pk_bf16(tp[0], tp[256]); o.y = cvt_pk_bf16(tp[512], tp[768]); o.z = cvt_pk_bf16(tp[1024], tp[1280]); o.w = cvt_pk_bf16(tp[1536], tp[1792]);
;             *(uint4*)(dst + (size_t)(n0 + nl) * K + k0 + 8 * q) = o; }
;         __syncthreads();
; __global__ __launch_bounds__(512, 2) void fwd_megakernel(Params p) {
;     ...
;           transpose_cvt<false, true>(p.w_ff1, Wff1T, DM, DFF, (float*)shm, ctr, slot0 + j, nslots); } }
.LBB0_39:
	s_ashr_i32 s14, s68, 31
	s_lshr_b32 s14, s14, 28
	s_add_i32 s14, s68, s14
	s_ashr_i32 s14, s14, 4
	s_lshl_b32 s71, s14, 10
	s_lshl_b32 s15, s14, 8
	s_sub_i32 s14, s69, s71
	v_add_u32_e32 v24, s14, v6
	v_or_b32_e32 v22, s15, v1
	v_add_u32_e32 v26, 8, v24
	v_add_u32_e32 v28, 16, v24
	v_add_u32_e32 v30, 24, v24
	v_add_u32_e32 v32, 32, v24
	v_add_u32_e32 v34, 40, v24
	v_add_u32_e32 v36, 48, v24
	v_add_u32_e32 v38, 56, v24
	v_ashrrev_i32_e32 v23, 31, v22
	v_ashrrev_i32_e32 v25, 31, v24
	v_ashrrev_i32_e32 v27, 31, v26
	v_ashrrev_i32_e32 v29, 31, v28
	v_ashrrev_i32_e32 v31, 31, v30
	v_ashrrev_i32_e32 v33, 31, v32
	v_ashrrev_i32_e32 v35, 31, v34
	v_ashrrev_i32_e32 v37, 31, v36
	v_ashrrev_i32_e32 v39, 31, v38
	v_lshl_add_u64 v[22:23], v[22:23], 2, s[30:31]
	v_lshlrev_b64 v[24:25], 14, v[24:25]
	v_lshlrev_b64 v[26:27], 14, v[26:27]
	v_lshlrev_b64 v[28:29], 14, v[28:29]
	v_lshlrev_b64 v[30:31], 14, v[30:31]
	v_lshlrev_b64 v[32:33], 14, v[32:33]
	v_lshlrev_b64 v[34:35], 14, v[34:35]
	v_lshlrev_b64 v[36:37], 14, v[36:37]
	v_lshlrev_b64 v[38:39], 14, v[38:39]
	v_lshl_add_u64 v[24:25], v[22:23], 0, v[24:25]
	v_lshl_add_u64 v[26:27], v[22:23], 0, v[26:27]
	v_lshl_add_u64 v[40:41], v[22:23], 0, v[28:29]
	v_lshl_add_u64 v[42:43], v[22:23], 0, v[30:31]
	v_lshl_add_u64 v[44:45], v[22:23], 0, v[32:33]
	v_lshl_add_u64 v[46:47], v[22:23], 0, v[34:35]
	v_lshl_add_u64 v[48:49], v[22:23], 0, v[36:37]
	v_lshl_add_u64 v[50:51], v[22:23], 0, v[38:39]
	global_load_dwordx4 v[22:25], v[24:25], off nt
	s_nop 0
	global_load_dwordx4 v[26:29], v[26:27], off nt
	s_nop 0
	global_load_dwordx4 v[30:33], v[40:41], off nt
	global_load_dwordx4 v[34:37], v[42:43], off nt
	s_nop 0
	global_load_dwordx4 v[38:41], v[44:45], off nt
	s_nop 0
	global_load_dwordx4 v[42:45], v[46:47], off nt
	s_nop 0
	global_load_dwordx4 v[46:49], v[48:49], off nt
	s_nop 0
	global_load_dwordx4 v[50:53], v[50:51], off nt
	v_lshrrev_b32_e32 v56, 5, v2
	v_lshl_add_u32 v54, v56, 6, v2
	v_lshl_add_u32 v54, v56, 5, v54
	v_add_u32_e32 v54, s15, v54
	v_add_u32_e32 v56, 32, v54
	v_add_u32_e32 v58, 64, v54
	v_add_u32_e32 v60, 0x60, v54
	s_ashr_i32 s15, s14, 31
	v_ashrrev_i32_e32 v55, 31, v54
	s_add_i32 s68, s68, s33
	s_add_i32 s69, s69, s70
	v_ashrrev_i32_e32 v57, 31, v56
	v_ashrrev_i32_e32 v59, 31, v58
	v_ashrrev_i32_e32 v61, 31, v60
	v_lshl_add_u64 v[62:63], s[14:15], 1, v[4:5]
	v_lshlrev_b64 v[54:55], 11, v[54:55]
	v_lshlrev_b64 v[56:57], 11, v[56:57]
	v_lshlrev_b64 v[58:59], 11, v[58:59]
	v_lshlrev_b64 v[60:61], 11, v[60:61]
	s_cmpk_lt_i32 s68, 0x100
	v_lshl_add_u64 v[54:55], v[62:63], 0, v[54:55]
	v_lshl_add_u64 v[56:57], v[62:63], 0, v[56:57]
	v_lshl_add_u64 v[58:59], v[62:63], 0, v[58:59]
	v_lshl_add_u64 v[60:61], v[62:63], 0, v[60:61]
	s_waitcnt vmcnt(7)
	ds_write_b128 v8, v[22:25]
	s_waitcnt vmcnt(6)
	ds_write_b128 v9, v[26:29]
	s_waitcnt vmcnt(5)
	ds_write_b128 v10, v[30:33]
	s_waitcnt vmcnt(4)
	ds_write_b128 v11, v[34:37]
	s_waitcnt vmcnt(3)
	ds_write_b128 v12, v[38:41]
	s_waitcnt vmcnt(2)
	ds_write_b128 v13, v[42:45]
	s_waitcnt vmcnt(1)
	ds_write_b128 v14, v[46:49]
	s_waitcnt vmcnt(0)
	ds_write_b128 v15, v[50:53]
	s_waitcnt lgkmcnt(0)
	s_barrier
	ds_read2st64_b32 v[22:23], v7 offset1:4
	ds_read2st64_b32 v[24:25], v7 offset0:8 offset1:12
	ds_read2st64_b32 v[26:27], v7 offset0:16 offset1:20
	ds_read2st64_b32 v[28:29], v7 offset0:24 offset1:28
	ds_read2st64_b32 v[30:31], v17 offset1:4
	ds_read2st64_b32 v[32:33], v17 offset0:8 offset1:12
	ds_read2st64_b32 v[34:35], v17 offset0:16 offset1:20
	ds_read2st64_b32 v[36:37], v17 offset0:24 offset1:28
	ds_read2st64_b32 v[38:39], v19 offset1:4
	ds_read2st64_b32 v[40:41], v19 offset0:8 offset1:12
	ds_read2st64_b32 v[42:43], v19 offset0:16 offset1:20
	ds_read2st64_b32 v[44:45], v19 offset0:24 offset1:28
	ds_read2st64_b32 v[46:47], v21 offset1:4
	ds_read2st64_b32 v[48:49], v21 offset0:8 offset1:12
	ds_read2st64_b32 v[50:51], v21 offset0:16 offset1:20
	ds_read2st64_b32 v[52:53], v21 offset0:24 offset1:28
	s_waitcnt lgkmcnt(14)
	v_cvt_pk_bf16_f32 v22, v22, v23
	v_cvt_pk_bf16_f32 v23, v24, v25
	s_waitcnt lgkmcnt(13)
	v_cvt_pk_bf16_f32 v24, v26, v27
	s_waitcnt lgkmcnt(12)
	v_cvt_pk_bf16_f32 v25, v28, v29
	s_waitcnt lgkmcnt(11)
	v_cvt_pk_bf16_f32 v26, v30, v31
	s_waitcnt lgkmcnt(10)
	v_cvt_pk_bf16_f32 v27, v32, v33
	s_waitcnt lgkmcnt(9)
	v_cvt_pk_bf16_f32 v28, v34, v35
	s_waitcnt lgkmcnt(8)
	v_cvt_pk_bf16_f32 v29, v36, v37
	s_waitcnt lgkmcnt(7)
	v_cvt_pk_bf16_f32 v30, v38, v39
	s_waitcnt lgkmcnt(6)
	v_cvt_pk_bf16_f32 v31, v40, v41
	s_waitcnt lgkmcnt(5)
	v_cvt_pk_bf16_f32 v32, v42, v43
	s_waitcnt lgkmcnt(4)
	v_cvt_pk_bf16_f32 v33, v44, v45
	s_waitcnt lgkmcnt(3)
	v_cvt_pk_bf16_f32 v34, v46, v47
	s_waitcnt lgkmcnt(2)
	v_cvt_pk_bf16_f32 v35, v48, v49
	s_waitcnt lgkmcnt(1)
	v_cvt_pk_bf16_f32 v36, v50, v51
	s_waitcnt lgkmcnt(0)
	v_cvt_pk_bf16_f32 v37, v52, v53
	global_store_dwordx4 v[54:55], v[22:25], off sc1
	global_store_dwordx4 v[56:57], v[26:29], off sc1
	global_store_dwordx4 v[58:59], v[30:33], off sc1
	global_store_dwordx4 v[60:61], v[34:37], off sc1
	s_barrier
	s_cbranch_scc1 .LBB0_39
	s_branch .LBB0_21
